# out-projection GEMMs of layers 0-2 split in two K halves (two bf16 partial slots summed and re-rounded to bf16 in the row phase); pool W_in transposes in idle CUs of the first out-projection phase
# speedup vs baseline: 1.0124x; 1.0026x over previous
; #define JW(gi, J0, J1, K, n0, n1) do { LAS unsigned char* p_ = lds + JOB_OFF + (gi) * 256; pg8::job_write(p_, J0); pg8::job_write(p_ + 128, J1); *(LAS int*)(p_ + 96) = (K); *(LAS int*)(p_ + 100) = (n0); *(LAS int*)(p_ + 104) = (n1); } while (0)
; __global__ void __launch_bounds__(NTHR, 2) fwd_mega(Args a0) {
;     ...
;     if (threadIdx.x == 0) {
;         unsigned char* ws = a0.ws;
;         bf16_t* H = (bf16_t*)(ws + WS_H); bf16_t* WIN = (bf16_t*)(ws + WS_WIN); bf16_t* WOUT = (bf16_t*)(ws + WS_WOUT); bf16_t* WG = (bf16_t*)(ws + WS_WG);
;         const float* LB = (const float*)(ws + WS_LB);
;         const int BIG = 1 << 30;
;     ...
;         const pg8::Job na0{H, WIN, 36, 48, BIG, 0, 4096, 0x271, SLW(0), SLW(1), SLW(2), nullptr, DI, nullptr, nullptr};
;         const pg8::Job na1{WIN + (size_t)12288 * DM, H, 16, 36, BIG, 0, BIG, 0x8, SLW(3), nullptr, nullptr, nullptr, MTOT, nullptr, nullptr};
;         const pg8::Job g2a{(const bf16_t*)SLW(4), WOUT, 36, 8, BIG, 0, BIG, 0x0, SLW(5), nullptr, nullptr, nullptr, DM, nullptr, nullptr};
;         const pg8::Job g2c{(const bf16_t*)SLW(0), WOUT, 36, 8, BIG, 0, BIG, 0x0, SLW(5), nullptr, nullptr, nullptr, DM, nullptr, nullptr};
;         const pg8::Job g2l{(const bf16_t*)SLW(4), WOUT, 32, 8, BIG, 0, BIG, 0x0, SLW(5), nullptr, nullptr, nullptr, DM, nullptr, nullptr};
;         const pg8::Job p0{H, WIN, 36, 32, BIG, 0, 4096, 0x20, SLW(0), SLW(2), nullptr, nullptr, DI, nullptr, nullptr};
;         const pg8::Job pg{(const bf16_t*)SLW(1), WG, 36, 16, 4, (size_t)MTOT * 1024, BIG, 0x6, SLW(4), nullptr, nullptr, nullptr, DI, a0.in[13], (const bf16_t*)SLW(2)};
;         const pg8::Job h0{H, WIN, 36, 64, BIG, 0, 4096, 0x2432, SLW(0), SLW(5), SLW(7), SLW(2), DI, LB, nullptr};
;         const pg8::Job h1{WIN + (size_t)16384 * DM, H, 16, 36, BIG, 0, BIG, 0x0, SLW(3), nullptr, nullptr, nullptr, MTOT, nullptr, nullptr};
;         JW(0, na0, na1, DM, 36 * 48, 16 * 36); JW(1, g2a, g2a, DI, 36 * 8, 0);
;         JW(2, p0, p0, DM, 36 * 32, 0); JW(3, pg, pg, 1024, 36 * 16, 0); JW(4, g2a, g2a, DI, 36 * 8, 0);
;         JW(5, h0, h1, DM, 36 * 64, 16 * 36); JW(6, g2c, g2c, DI, 36 * 8, 0);
;         JW(7, na0, na1, DM, 36 * 48, 16 * 36); JW(8, g2l, g2l, DI, 32 * 8, 0);
.LBB0_14:
	s_mov_b32 s30, 0
	v_cmp_eq_u32_e64 s[2:3], 0, v195
	s_mov_b64 s[34:35], exec
	s_nop 0
	v_writelane_b32 v252, s2, 4
	s_nop 1
	v_writelane_b32 v252, s3, 5
	s_and_b64 s[2:3], s[34:35], s[2:3]
	s_mov_b64 exec, s[2:3]
	s_cbranch_execz .LBB0_16
	s_load_dwordx4 s[4:7], s[0:1], 0xa0
	s_load_dwordx2 s[40:41], s[0:1], 0x68
	s_waitcnt lgkmcnt(0)
	s_movk_i32 s7, 0x1000
	s_mov_b32 s6, 2.0
	s_mov_b32 s31, s30
	s_add_u32 s24, s4, 0xa00000
	s_addc_u32 s25, s5, 0
	s_add_u32 s26, s4, 0x2e00000
	s_addc_u32 s27, s5, 0
	s_add_u32 s14, s4, 0x7e00000
	s_addc_u32 s15, s5, 0
	s_add_u32 s46, s4, 0x8e00000
	s_addc_u32 s47, s5, 0
	s_add_u32 s2, s4, 0x180000
	s_addc_u32 s3, s5, 0
	s_add_u32 s16, s4, 0x9600000
	s_addc_u32 s17, s5, 0
	s_add_u32 s18, s4, 0xde00000
	s_addc_u32 s19, s5, 0
	s_add_u32 s28, s4, 0x12600000
	s_addc_u32 s29, s5, 0
	s_add_u32 s20, s4, 0x5e00000
	s_addc_u32 s21, s5, 0
	s_add_u32 s52, s4, 0x16e00000
	s_addc_u32 s53, s5, 0
	s_add_u32 s12, s4, 0x1b600000
	s_addc_u32 s13, s5, 0
	s_add_u32 s36, s4, 0x1fe00000
	s_addc_u32 s37, s5, 0
	s_add_u32 s10, s4, 0x28e00000
	s_addc_u32 s11, s5, 0
	s_add_u32 s8, s4, 0x6e00000
	s_addc_u32 s9, s5, 0
	s_add_i32 s4, 0, 0x23000
	v_mov_b64_e32 v[8:9], s[24:25]
	v_mov_b32_e32 v0, s4
	v_mov_b64_e32 v[10:11], s[26:27]
	s_mov_b32 s5, 48
	s_mov_b32 s4, 36
	s_add_i32 s22, 0, 0x23010
	v_mov_b64_e32 v[14:15], s[6:7]
	ds_write_b128 v0, v[8:11]
	v_mov_b32_e32 v0, s22
	v_mov_b64_e32 v[12:13], s[4:5]
	s_add_i32 s5, 0, 0x23020
	ds_write_b128 v0, v[12:15]
	v_mov_b32_e32 v0, s5
	v_mov_b64_e32 v[56:57], s[30:31]
	s_movk_i32 s23, 0x271
	s_mov_b32 s22, s7
	s_add_i32 s5, 0, 0x23028
	ds_write_b64 v0, v[56:57]
	v_mov_b32_e32 v0, s5
	v_mov_b64_e32 v[58:59], s[22:23]
	s_add_i32 s5, 0, 0x23030
	v_mov_b64_e32 v[16:17], s[16:17]
	ds_write_b64 v0, v[58:59]
	v_mov_b32_e32 v0, s5
	v_mov_b64_e32 v[18:19], s[18:19]
	s_add_i32 s5, 0, 0x23040
	v_mov_b64_e32 v[20:21], s[28:29]
	s_mov_b32 s48, s30
	s_mov_b32 s49, s30
	ds_write_b128 v0, v[16:19]
	v_mov_b32_e32 v0, s5
	v_mov_b64_e32 v[22:23], s[30:31]
	s_add_i32 s5, 0, 0x23050
	s_mov_b32 s50, s30
	s_mov_b32 s51, s30
	v_mov_b64_e32 v[4:5], s[48:49]
	s_mov_b32 s22, s24
	s_mov_b32 s23, s25
	ds_write_b128 v0, v[20:23]
	v_mov_b32_e32 v0, s5
	v_mov_b64_e32 v[6:7], s[50:51]
	s_add_i32 s5, 0, 0x23080
	v_mov_b64_e32 v[26:27], s[22:23]
	s_mov_b32 s48, 16
	s_mov_b32 s49, s4
	ds_write_b128 v0, v[4:7]
	v_mov_b32_e32 v0, s5
	v_mov_b64_e32 v[24:25], s[20:21]
	s_movk_i32 s51, 0x2400
	s_mov_b32 s50, s6
	s_add_i32 s5, 0, 0x23090
	v_mov_b64_e32 v[32:33], s[48:49]
	ds_write_b128 v0, v[24:27]
	v_mov_b32_e32 v0, s5
	v_mov_b64_e32 v[34:35], s[50:51]
	s_add_i32 s5, 0, 0x230a0
	ds_write_b128 v0, v[32:35]
	v_mov_b32_e32 v0, s5
	s_mov_b32 s21, 8
	s_mov_b32 s20, s6
	s_add_i32 s5, 0, 0x230a8
	ds_write_b64 v0, v[56:57]
	v_mov_b32_e32 v0, s5
	v_mov_b64_e32 v[60:61], s[20:21]
	s_mov_b32 s54, s30
	s_mov_b32 s55, s30
	s_add_i32 s5, 0, 0x230b0
	v_mov_b64_e32 v[36:37], s[52:53]
	ds_write_b64 v0, v[60:61]
	v_mov_b32_e32 v0, s5
	v_mov_b64_e32 v[38:39], s[54:55]
	s_add_i32 s5, 0, 0x230c0
	ds_write_b128 v0, v[36:39]
	v_mov_b32_e32 v0, s5
	s_add_i32 s5, 0, 0x230d0
	s_movk_i32 s52, 0x800
	ds_write_b128 v0, v[4:7]
	v_mov_b32_e32 v0, s5
	s_movk_i32 s54, 0x240
	s_movk_i32 s53, 0x6c0
	s_add_i32 s5, 0, 0x23060
	v_mov_b32_e32 v48, s52
	ds_write_b128 v0, v[4:7]
	v_mov_b32_e32 v0, s5
	v_mov_b32_e32 v49, s53
	v_mov_b32_e32 v50, s54
	s_add_i32 s5, 0, 0x23100
	v_mov_b64_e32 v[30:31], s[14:15]
	s_mov_b32 s22, s6
	s_mov_b32 s23, s52
	ds_write_b96 v0, v[48:50]
	v_mov_b32_e32 v0, s5
	v_mov_b64_e32 v[28:29], s[12:13]
	s_mov_b32 s20, s4
	s_add_i32 s5, 0, 0x23110
	v_mov_b64_e32 v[46:47], s[22:23]
	ds_write_b128 v0, v[28:31]
	v_mov_b32_e32 v0, s5
	v_mov_b64_e32 v[44:45], s[20:21]
	s_add_i32 s5, 0, 0x23120
	ds_write_b128 v0, v[44:47]
	v_mov_b32_e32 v0, s5
	s_mov_b32 s23, s30
	s_add_i32 s5, 0, 0x23128
	s_mov_b32 s38, s30
	s_mov_b32 s39, s30
	ds_write_b64 v0, v[56:57]
	v_mov_b32_e32 v0, s5
	v_mov_b64_e32 v[62:63], s[22:23]
	s_add_i32 s5, 0, 0x23130
	v_mov_b64_e32 v[42:43], s[38:39]
	ds_write_b64 v0, v[62:63]
	v_mov_b32_e32 v0, s5
	v_mov_b64_e32 v[40:41], s[36:37]
	s_add_i32 s5, 0, 0x23140
	ds_write_b128 v0, v[40:43]
	v_mov_b32_e32 v0, s5
	s_add_i32 s5, 0, 0x23150
	ds_write_b128 v0, v[4:7]
	v_mov_b32_e32 v0, s5
	s_add_i32 s5, 0, 0x23180
	ds_write_b128 v0, v[4:7]
	v_mov_b32_e32 v0, s5
	s_add_i32 s5, 0, 0x23190
	ds_write_b128 v0, v[28:31]
	v_mov_b32_e32 v0, s5
	s_add_i32 s5, 0, 0x231a0
	ds_write_b128 v0, v[44:47]
	v_mov_b32_e32 v0, s5
	s_add_i32 s5, 0, 0x231a8
	ds_write_b64 v0, v[56:57]
	v_mov_b32_e32 v0, s5
	s_add_i32 s5, 0, 0x231b0
	ds_write_b64 v0, v[62:63]
	v_mov_b32_e32 v0, s5
	s_add_i32 s5, 0, 0x231c0
	ds_write_b128 v0, v[40:43]
	v_mov_b32_e32 v0, s5
	s_add_i32 s5, 0, 0x231d0
	s_mov_b32 s56, s7
	ds_write_b128 v0, v[4:7]
	v_mov_b32_e32 v0, s5
	s_movk_i32 s57, 0x120
	s_mov_b32 s58, s30
	s_add_i32 s5, 0, 0x23160
	v_mov_b32_e32 v52, s56
	ds_write_b128 v0, v[4:7]
	v_mov_b32_e32 v0, s5
	v_mov_b32_e32 v53, s57
	v_mov_b32_e32 v54, s58
	s_add_i32 s5, 0, 0x23200
	ds_write_b96 v0, v[52:54]
	v_mov_b32_e32 v0, s5
	s_mov_b32 s5, 32
	s_add_i32 s20, 0, 0x23210
	v_mov_b64_e32 v[66:67], s[6:7]
	ds_write_b128 v0, v[8:11]
	v_mov_b32_e32 v0, s20
	v_mov_b64_e32 v[64:65], s[4:5]
	s_add_i32 s20, 0, 0x23220
	s_mov_b64 s[58:59], s[18:19]
	ds_write_b128 v0, v[64:67]
	v_mov_b32_e32 v0, s20
	s_mov_b32 s22, s7
	s_mov_b32 s23, s5
	s_add_i32 s20, 0, 0x23228
	s_mov_b32 s58, s28
	s_mov_b32 s59, s29
	ds_write_b64 v0, v[56:57]
	v_mov_b32_e32 v0, s20
	v_mov_b64_e32 v[2:3], s[22:23]
	s_mov_b64 s[56:57], s[16:17]
	s_add_i32 s20, 0, 0x23230
	v_mov_b64_e32 v[70:71], s[58:59]
	ds_write_b64 v0, v[2:3]
; #define JW(gi, J0, J1, K, n0, n1) do { LAS unsigned char* p_ = lds + JOB_OFF + (gi) * 256; pg8::job_write(p_, J0); pg8::job_write(p_ + 128, J1); *(LAS int*)(p_ + 96) = (K); *(LAS int*)(p_ + 100) = (n0); *(LAS int*)(p_ + 104) = (n1); } while (0)
; __global__ void __launch_bounds__(NTHR, 2) fwd_mega(Args a0) {
;     ...
;         const pg8::Job na0{H, WIN, 36, 48, BIG, 0, 4096, 0x271, SLW(0), SLW(1), SLW(2), nullptr, DI, nullptr, nullptr};
;         const pg8::Job na1{WIN + (size_t)12288 * DM, H, 16, 36, BIG, 0, BIG, 0x8, SLW(3), nullptr, nullptr, nullptr, MTOT, nullptr, nullptr};
;         const pg8::Job g2a{(const bf16_t*)SLW(4), WOUT, 36, 8, BIG, 0, BIG, 0x0, SLW(5), nullptr, nullptr, nullptr, DM, nullptr, nullptr};
;         const pg8::Job g2c{(const bf16_t*)SLW(0), WOUT, 36, 8, BIG, 0, BIG, 0x0, SLW(5), nullptr, nullptr, nullptr, DM, nullptr, nullptr};
;         const pg8::Job g2l{(const bf16_t*)SLW(4), WOUT, 32, 8, BIG, 0, BIG, 0x0, SLW(5), nullptr, nullptr, nullptr, DM, nullptr, nullptr};
;         const pg8::Job p0{H, WIN, 36, 32, BIG, 0, 4096, 0x20, SLW(0), SLW(2), nullptr, nullptr, DI, nullptr, nullptr};
;         const pg8::Job pg{(const bf16_t*)SLW(1), WG, 36, 16, 4, (size_t)MTOT * 1024, BIG, 0x6, SLW(4), nullptr, nullptr, nullptr, DI, a0.in[13], (const bf16_t*)SLW(2)};
;         const pg8::Job h0{H, WIN, 36, 64, BIG, 0, 4096, 0x2432, SLW(0), SLW(5), SLW(7), SLW(2), DI, LB, nullptr};
;         const pg8::Job h1{WIN + (size_t)16384 * DM, H, 16, 36, BIG, 0, BIG, 0x0, SLW(3), nullptr, nullptr, nullptr, MTOT, nullptr, nullptr};
;         JW(0, na0, na1, DM, 36 * 48, 16 * 36); JW(1, g2a, g2a, DI, 36 * 8, 0);
;         JW(2, p0, p0, DM, 36 * 32, 0); JW(3, pg, pg, 1024, 36 * 16, 0); JW(4, g2a, g2a, DI, 36 * 8, 0);
;         JW(5, h0, h1, DM, 36 * 64, 16 * 36); JW(6, g2c, g2c, DI, 36 * 8, 0);
;         JW(7, na0, na1, DM, 36 * 48, 16 * 36); JW(8, g2l, g2l, DI, 32 * 8, 0);
	v_mov_b32_e32 v0, s20
	v_mov_b64_e32 v[68:69], s[56:57]
	s_add_i32 s20, 0, 0x23240
	ds_write_b128 v0, v[68:71]
	v_mov_b32_e32 v0, s20
	s_add_i32 s20, 0, 0x23250
	ds_write_b128 v0, v[4:7]
	v_mov_b32_e32 v0, s20
	s_add_i32 s20, 0, 0x23280
	ds_write_b128 v0, v[4:7]
	v_mov_b32_e32 v0, s20
	s_add_i32 s20, 0, 0x23290
	ds_write_b128 v0, v[8:11]
	v_mov_b32_e32 v0, s20
	s_add_i32 s20, 0, 0x232a0
	ds_write_b128 v0, v[64:67]
	v_mov_b32_e32 v0, s20
	s_add_i32 s20, 0, 0x232a8
	ds_write_b64 v0, v[56:57]
	v_mov_b32_e32 v0, s20
	s_add_i32 s20, 0, 0x232b0
	ds_write_b64 v0, v[2:3]
	v_mov_b32_e32 v0, s20
	s_add_i32 s20, 0, 0x232c0
	ds_write_b128 v0, v[68:71]
	v_mov_b32_e32 v0, s20
	s_add_i32 s20, 0, 0x232d0
	ds_write_b128 v0, v[4:7]
	v_mov_b32_e32 v0, s20
	s_add_i32 s20, 0, 0x23260
	s_mov_b32 s44, s18
	s_mov_b32 s45, s19
	v_mov_b64_e32 v[66:67], s[46:47]
	ds_write_b128 v0, v[4:7]
	v_mov_b32_e32 v0, 0x800
	v_mov_b32_e32 v1, 0x480
	v_mov_b32_e32 v2, 0
	v_mov_b32_e32 v3, s20
	s_add_i32 s18, 0, 0x23300
	v_mov_b64_e32 v[64:65], s[44:45]
	s_mov_b32 s46, 4
	s_mov_b32 s47, s7
	ds_write_b96 v3, v[0:2]
	v_mov_b32_e32 v1, s18
	s_mov_b32 s44, s4
	s_mov_b32 s45, s48
	s_add_i32 s4, 0, 0x23310
	v_mov_b64_e32 v[70:71], s[46:47]
	ds_write_b128 v1, v[64:67]
	v_mov_b32_e32 v1, s4
	v_mov_b64_e32 v[68:69], s[44:45]
	s_add_i32 s4, 0, 0x23320
	s_mov_b32 s18, 0x900000
	s_mov_b32 s19, s30
	s_mov_b64 s[46:47], s[14:15]
	ds_write_b128 v1, v[68:71]
	v_mov_b32_e32 v1, s4
	v_mov_b64_e32 v[80:81], s[18:19]
	s_mov_b32 s7, 6
	s_add_i32 s4, 0, 0x23328
	s_mov_b32 s46, s30
	s_mov_b32 s47, s30
	ds_write_b64 v1, v[80:81]
	v_mov_b32_e32 v1, s4
	v_mov_b64_e32 v[82:83], s[6:7]
	s_mov_b64 s[44:45], s[12:13]
	s_add_i32 s4, 0, 0x23330
	v_mov_b64_e32 v[74:75], s[46:47]
	ds_write_b64 v1, v[82:83]
	v_mov_b32_e32 v1, s4
	v_mov_b64_e32 v[72:73], s[44:45]
	s_add_i32 s4, 0, 0x23340
	s_mov_b32 s42, s28
	s_mov_b32 s43, s29
	ds_write_b128 v1, v[72:75]
	v_mov_b32_e32 v1, s4
	s_add_i32 s4, 0, 0x23350
	v_mov_b64_e32 v[78:79], s[42:43]
	ds_write_b128 v1, v[4:7]
	v_mov_b32_e32 v1, s4
	v_mov_b64_e32 v[76:77], s[40:41]
	s_add_i32 s4, 0, 0x23380
	ds_write_b128 v1, v[76:79]
	v_mov_b32_e32 v1, s4
	s_add_i32 s4, 0, 0x23390
	ds_write_b128 v1, v[64:67]
	v_mov_b32_e32 v1, s4
	s_add_i32 s4, 0, 0x233a0
	ds_write_b128 v1, v[68:71]
	v_mov_b32_e32 v1, s4
	s_add_i32 s4, 0, 0x233a8
	ds_write_b64 v1, v[80:81]
	v_mov_b32_e32 v1, s4
	s_add_i32 s4, 0, 0x233b0
	ds_write_b64 v1, v[82:83]
	v_mov_b32_e32 v1, s4
	s_add_i32 s4, 0, 0x233c0
	ds_write_b128 v1, v[72:75]
	v_mov_b32_e32 v1, s4
	s_add_i32 s4, 0, 0x233d0
	ds_write_b128 v1, v[4:7]
	v_mov_b32_e32 v1, s4
	s_add_i32 s4, 0, 0x23360
	ds_write_b128 v1, v[76:79]
	v_mov_b32_e32 v72, 0x400
	v_mov_b32_e32 v73, 0x240
	v_mov_b32_e32 v74, v2
	v_mov_b32_e32 v1, s4
	s_add_i32 s4, 0, 0x23400
	ds_write_b96 v1, v[72:74]
	v_mov_b32_e32 v1, s4
	s_add_i32 s4, 0, 0x23410
	ds_write_b128 v1, v[28:31]
	v_mov_b32_e32 v1, s4
	s_add_i32 s4, 0, 0x23420
	ds_write_b128 v1, v[44:47]
	v_mov_b32_e32 v1, s4
	s_add_i32 s4, 0, 0x23428
	ds_write_b64 v1, v[56:57]
	v_mov_b32_e32 v1, s4
	s_add_i32 s4, 0, 0x23430
	ds_write_b64 v1, v[62:63]
	v_mov_b32_e32 v1, s4
	s_add_i32 s4, 0, 0x23440
	ds_write_b128 v1, v[40:43]
	v_mov_b32_e32 v1, s4
	s_add_i32 s4, 0, 0x23450
	ds_write_b128 v1, v[4:7]
	v_mov_b32_e32 v1, s4
	s_add_i32 s4, 0, 0x23480
	ds_write_b128 v1, v[4:7]
	v_mov_b32_e32 v1, s4
	s_add_i32 s4, 0, 0x23490
	ds_write_b128 v1, v[28:31]
	v_mov_b32_e32 v1, s4
	s_add_i32 s4, 0, 0x234a0
	ds_write_b128 v1, v[44:47]
	v_mov_b32_e32 v1, s4
	s_add_i32 s4, 0, 0x234a8
	ds_write_b64 v1, v[56:57]
	v_mov_b32_e32 v1, s4
	s_add_i32 s4, 0, 0x234b0
	ds_write_b64 v1, v[62:63]
	v_mov_b32_e32 v1, s4
	s_add_i32 s4, 0, 0x234c0
	ds_write_b128 v1, v[40:43]
	v_mov_b32_e32 v1, s4
	s_add_i32 s4, 0, 0x234d0
	ds_write_b128 v1, v[4:7]
	v_mov_b32_e32 v1, s4
	s_add_i32 s4, 0, 0x23460
	ds_write_b128 v1, v[4:7]
	v_mov_b32_e32 v1, s4
	s_add_i32 s4, 0, 0x23500
	ds_write_b96 v1, v[52:54]
	v_mov_b32_e32 v1, s4
	s_add_i32 s4, 0, 0x23510
	ds_write_b128 v1, v[8:11]
	v_mov_b32_e32 v64, 36
	v_mov_b32_e32 v65, 64
	v_mov_b32_e32 v66, 2.0
	v_mov_b32_e32 v67, 0x1000
	v_mov_b32_e32 v1, s4
	s_add_i32 s4, 0, 0x23520
	ds_write_b128 v1, v[64:67]
	v_mov_b32_e32 v1, s4
	s_add_i32 s4, 0, 0x23528
	s_mov_b32 s18, s36
	s_mov_b32 s19, s37
	ds_write_b64 v1, v[56:57]
	v_mov_b32_e32 v65, 0x2432
	v_mov_b32_e32 v64, v67
	v_mov_b32_e32 v1, s4
	s_add_i32 s4, 0, 0x23530
	v_mov_b64_e32 v[70:71], s[18:19]
	ds_write_b64 v1, v[64:65]
	v_mov_b32_e32 v1, s4
	v_mov_b64_e32 v[68:69], s[16:17]
	s_add_i32 s4, 0, 0x23540
	ds_write_b128 v1, v[68:71]
	v_mov_b32_e32 v68, s10
	v_mov_b32_e32 v69, s11
	v_mov_b32_e32 v70, s28
	v_mov_b32_e32 v71, s29
	v_mov_b32_e32 v1, s4
	ds_write_b128 v1, v[68:71]
	v_mov_b32_e32 v68, s2
	s_add_i32 s2, 0, 0x23550
	v_mov_b32_e32 v69, s3
	v_mov_b32_e32 v70, v2
	v_mov_b32_e32 v71, v2
	v_mov_b32_e32 v1, s2
	s_add_i32 s2, 0, 0x23580
	ds_write_b128 v1, v[68:71]
	v_mov_b32_e32 v68, s8
	v_mov_b32_e32 v69, s9
	v_mov_b32_e32 v70, s24
	v_mov_b32_e32 v71, s25
	v_mov_b32_e32 v1, s2
	s_add_i32 s2, 0, 0x23590
	ds_write_b128 v1, v[68:71]
	v_mov_b32_e32 v1, s2
	s_add_i32 s2, 0, 0x235a0
; #define JW(gi, J0, J1, K, n0, n1) do { LAS unsigned char* p_ = lds + JOB_OFF + (gi) * 256; pg8::job_write(p_, J0); pg8::job_write(p_ + 128, J1); *(LAS int*)(p_ + 96) = (K); *(LAS int*)(p_ + 100) = (n0); *(LAS int*)(p_ + 104) = (n1); } while (0)
; __global__ void __launch_bounds__(NTHR, 2) fwd_mega(Args a0) {
;     ...
;         const pg8::Job na0{H, WIN, 36, 48, BIG, 0, 4096, 0x271, SLW(0), SLW(1), SLW(2), nullptr, DI, nullptr, nullptr};
;         const pg8::Job na1{WIN + (size_t)12288 * DM, H, 16, 36, BIG, 0, BIG, 0x8, SLW(3), nullptr, nullptr, nullptr, MTOT, nullptr, nullptr};
;         const pg8::Job g2a{(const bf16_t*)SLW(4), WOUT, 36, 8, BIG, 0, BIG, 0x0, SLW(5), nullptr, nullptr, nullptr, DM, nullptr, nullptr};
;         const pg8::Job g2c{(const bf16_t*)SLW(0), WOUT, 36, 8, BIG, 0, BIG, 0x0, SLW(5), nullptr, nullptr, nullptr, DM, nullptr, nullptr};
;         const pg8::Job g2l{(const bf16_t*)SLW(4), WOUT, 32, 8, BIG, 0, BIG, 0x0, SLW(5), nullptr, nullptr, nullptr, DM, nullptr, nullptr};
;         const pg8::Job p0{H, WIN, 36, 32, BIG, 0, 4096, 0x20, SLW(0), SLW(2), nullptr, nullptr, DI, nullptr, nullptr};
;         const pg8::Job pg{(const bf16_t*)SLW(1), WG, 36, 16, 4, (size_t)MTOT * 1024, BIG, 0x6, SLW(4), nullptr, nullptr, nullptr, DI, a0.in[13], (const bf16_t*)SLW(2)};
;         const pg8::Job h0{H, WIN, 36, 64, BIG, 0, 4096, 0x2432, SLW(0), SLW(5), SLW(7), SLW(2), DI, LB, nullptr};
;         const pg8::Job h1{WIN + (size_t)16384 * DM, H, 16, 36, BIG, 0, BIG, 0x0, SLW(3), nullptr, nullptr, nullptr, MTOT, nullptr, nullptr};
;         JW(0, na0, na1, DM, 36 * 48, 16 * 36); JW(1, g2a, g2a, DI, 36 * 8, 0);
;         JW(2, p0, p0, DM, 36 * 32, 0); JW(3, pg, pg, 1024, 36 * 16, 0); JW(4, g2a, g2a, DI, 36 * 8, 0);
;         JW(5, h0, h1, DM, 36 * 64, 16 * 36); JW(6, g2c, g2c, DI, 36 * 8, 0);
;         JW(7, na0, na1, DM, 36 * 48, 16 * 36); JW(8, g2l, g2l, DI, 32 * 8, 0);
	ds_write_b128 v1, v[32:35]
	v_mov_b32_e32 v1, s2
	s_add_i32 s2, 0, 0x235a8
	ds_write_b64 v1, v[56:57]
	v_mov_b32_e32 v1, s2
	s_add_i32 s2, 0, 0x235b0
	ds_write_b64 v1, v[62:63]
	v_mov_b32_e32 v1, s2
	s_add_i32 s2, 0, 0x235c0
	ds_write_b128 v1, v[36:39]
	v_mov_b32_e32 v1, s2
	s_add_i32 s2, 0, 0x235d0
	ds_write_b128 v1, v[4:7]
	v_mov_b32_e32 v1, s2
	s_add_i32 s2, 0, 0x23560
	s_mov_b32 s18, s14
	s_mov_b32 s19, s15
	v_mov_b32_e32 v65, 0x900
	v_mov_b32_e32 v64, v0
	v_mov_b32_e32 v66, v73
	v_mov_b32_e32 v0, s2
	s_add_i32 s2, 0, 0x23600
	v_mov_b64_e32 v[70:71], s[18:19]
	ds_write_b96 v0, v[64:66]
	v_mov_b32_e32 v0, s2
	v_mov_b64_e32 v[68:69], s[16:17]
	s_add_i32 s2, 0, 0x23610
	ds_write_b128 v0, v[68:71]
	v_mov_b32_e32 v0, s2
	s_add_i32 s2, 0, 0x23620
	ds_write_b128 v0, v[44:47]
	v_mov_b32_e32 v0, s2
	s_add_i32 s2, 0, 0x23628
	ds_write_b64 v0, v[56:57]
	v_mov_b32_e32 v0, s2
	s_add_i32 s2, 0, 0x23630
	ds_write_b64 v0, v[62:63]
	v_mov_b32_e32 v0, s2
	s_add_i32 s2, 0, 0x23640
	ds_write_b128 v0, v[40:43]
	v_mov_b32_e32 v0, s2
	s_add_i32 s2, 0, 0x23650
	ds_write_b128 v0, v[4:7]
	v_mov_b32_e32 v0, s2
	s_add_i32 s2, 0, 0x23680
	ds_write_b128 v0, v[4:7]
	v_mov_b32_e32 v0, s2
	s_add_i32 s2, 0, 0x23690
	ds_write_b128 v0, v[68:71]
	v_mov_b32_e32 v0, s2
	s_add_i32 s2, 0, 0x236a0
	ds_write_b128 v0, v[44:47]
	v_mov_b32_e32 v0, s2
	s_add_i32 s2, 0, 0x236a8
	ds_write_b64 v0, v[56:57]
	v_mov_b32_e32 v0, s2
	s_add_i32 s2, 0, 0x236b0
	ds_write_b64 v0, v[62:63]
	v_mov_b32_e32 v0, s2
	s_add_i32 s2, 0, 0x236c0
	ds_write_b128 v0, v[40:43]
	v_mov_b32_e32 v0, s2
	s_add_i32 s2, 0, 0x236d0
	ds_write_b128 v0, v[4:7]
	v_mov_b32_e32 v0, s2
	s_add_i32 s2, 0, 0x23660
	ds_write_b128 v0, v[4:7]
	v_mov_b32_e32 v0, s2
	s_add_i32 s2, 0, 0x23700
	ds_write_b96 v0, v[52:54]
	v_mov_b32_e32 v0, s2
	s_add_i32 s2, 0, 0x23710
	ds_write_b128 v0, v[8:11]
	v_mov_b32_e32 v0, s2
	s_add_i32 s2, 0, 0x23720
	ds_write_b128 v0, v[12:15]
	v_mov_b32_e32 v0, s2
	s_add_i32 s2, 0, 0x23728
	ds_write_b64 v0, v[56:57]
	v_mov_b32_e32 v0, s2
	s_add_i32 s2, 0, 0x23730
	ds_write_b64 v0, v[58:59]
	v_mov_b32_e32 v0, s2
	s_add_i32 s2, 0, 0x23740
	ds_write_b128 v0, v[16:19]
	v_mov_b32_e32 v0, s2
	s_add_i32 s2, 0, 0x23750
	ds_write_b128 v0, v[20:23]
	v_mov_b32_e32 v0, s2
	s_add_i32 s2, 0, 0x23780
	ds_write_b128 v0, v[4:7]
	v_mov_b32_e32 v0, s2
	s_add_i32 s2, 0, 0x23790
	ds_write_b128 v0, v[24:27]
	v_mov_b32_e32 v0, s2
	s_add_i32 s2, 0, 0x237a0
	ds_write_b128 v0, v[32:35]
	v_mov_b32_e32 v0, s2
	s_add_i32 s2, 0, 0x237a8
	ds_write_b64 v0, v[56:57]
	v_mov_b32_e32 v0, s2
	s_add_i32 s2, 0, 0x237b0
	ds_write_b64 v0, v[60:61]
	v_mov_b32_e32 v0, s2
	s_add_i32 s2, 0, 0x237c0
	ds_write_b128 v0, v[36:39]
	v_mov_b32_e32 v0, s2
	s_add_i32 s2, 0, 0x237d0
	ds_write_b128 v0, v[4:7]
	v_mov_b32_e32 v0, s2
	s_add_i32 s2, 0, 0x23760
	ds_write_b128 v0, v[4:7]
	v_mov_b32_e32 v0, s2
	s_add_i32 s2, 0, 0x23800
	s_mov_b32 s20, s5
	ds_write_b96 v0, v[48:50]
	v_mov_b32_e32 v0, s2
	s_mov_b32 s22, s6
	s_mov_b32 s23, s52
	s_add_i32 s2, 0, 0x23810
	v_mov_b64_e32 v[8:9], s[20:21]
	ds_write_b128 v0, v[28:31]
	v_mov_b32_e32 v0, s2
	v_mov_b64_e32 v[10:11], s[22:23]
	s_add_i32 s2, 0, 0x23820
	ds_write_b128 v0, v[8:11]
	v_mov_b32_e32 v0, s2
	s_add_i32 s2, 0, 0x23828
	ds_write_b64 v0, v[56:57]
	v_mov_b32_e32 v0, s2
	s_add_i32 s2, 0, 0x23830
	ds_write_b64 v0, v[62:63]
	v_mov_b32_e32 v0, s2
	s_add_i32 s2, 0, 0x23840
	ds_write_b128 v0, v[40:43]
	v_mov_b32_e32 v0, s2
	s_add_i32 s2, 0, 0x23850
	ds_write_b128 v0, v[4:7]
	v_mov_b32_e32 v0, s2
	s_add_i32 s2, 0, 0x23880
	ds_write_b128 v0, v[4:7]
	v_mov_b32_e32 v0, s2
	s_add_i32 s2, 0, 0x23890
	ds_write_b128 v0, v[28:31]
	v_mov_b32_e32 v0, s2
	s_add_i32 s2, 0, 0x238a0
	ds_write_b128 v0, v[8:11]
	v_mov_b32_e32 v0, s2
	s_add_i32 s2, 0, 0x238a8
	ds_write_b64 v0, v[56:57]
	v_mov_b32_e32 v0, s2
	s_add_i32 s2, 0, 0x238b0
	ds_write_b64 v0, v[62:63]
	v_mov_b32_e32 v0, s2
	s_add_i32 s2, 0, 0x238c0
	ds_write_b128 v0, v[40:43]
	v_mov_b32_e32 v0, s2
	s_add_i32 s2, 0, 0x238d0
	ds_write_b128 v0, v[4:7]
	v_mov_b32_e32 v0, s2
	s_add_i32 s2, 0, 0x23860
	ds_write_b128 v1, v[4:7]
	ds_write_b128 v0, v[4:7]
	v_mov_b32_e32 v1, 0x100
	v_mov_b32_e32 v0, v67
	v_mov_b32_e32 v3, s2
	ds_write_b96 v3, v[0:2]
	v_readlane_b32 s4, v252, 0
	v_readlane_b32 s5, v252, 1
	s_add_u32 s6, s4, 0x1b601000
	s_addc_u32 s7, s5, 0
	s_add_u32 s8, s4, 0x7e01000
	s_addc_u32 s9, s5, 0
	s_add_u32 s10, s4, 0x24600000
	s_addc_u32 s11, s5, 0
	v_mov_b32_e32 v0, s6
	v_mov_b32_e32 v1, s7
	v_mov_b32_e32 v2, s8
	v_mov_b32_e32 v3, s9
	v_mov_b32_e32 v4, s10
	v_mov_b32_e32 v5, s11
	v_mov_b32_e32 v6, 0x120
	v_mov_b32_e32 v7, 0x100
	s_add_u32 s6, s4, 0x9601000
	s_addc_u32 s7, s5, 0
	v_mov_b32_e32 v8, s6
	v_mov_b32_e32 v9, s7
	v_mov_b32_e32 v10, s8
	v_mov_b32_e32 v11, s9
	v_mov_b32_e32 v12, 0x23100
	ds_write_b128 v12, v[0:3] offset:128
	ds_write_b64 v12, v[4:5] offset:176
	ds_write_b32 v12, v6 offset:104
	v_mov_b32_e32 v12, 0x23400
	ds_write_b128 v12, v[0:3] offset:128
	ds_write_b64 v12, v[4:5] offset:176
	ds_write_b32 v12, v6 offset:104
	v_mov_b32_e32 v12, 0x23600
	ds_write_b128 v12, v[8:11] offset:128
	ds_write_b64 v12, v[4:5] offset:176
	ds_write_b32 v12, v6 offset:104

; __device__ __forceinline__ float bflo(unsigned w) { return __uint_as_float(w << 16); }
; __device__ __forceinline__ float bfhi(unsigned w) { return __uint_as_float(w & 0xffff0000u); }
; __device__ __forceinline__ void row_phase(const Args& a, int li, LAS unsigned char* lds, int G, int tid, int wave, int lane) {
;     ...
;                 const bf16_t* yrow = Y + (size_t)row * DM;
;                 u32x2 yw[8];
; #pragma unroll
;                 for (int j = 0; j < 8; ++j) xv[j] = *(const f32x4*)(xrow + 4 * lane + 256 * j);
; #pragma unroll
;                 for (int j = 0; j < 8; ++j) yw[j] = *(const u32x2*)(yrow + 4 * lane + 256 * j);
;                 f32x4 yv[8]; float ss = 0.f;
; #pragma unroll
;                 for (int j = 0; j < 8; ++j) { yv[j] = (f32x4){bflo(yw[j].x), bfhi(yw[j].x), bflo(yw[j].y), bfhi(yw[j].y)}; ss += (yv[j].x * yv[j].x + yv[j].y * yv[j].y) + (yv[j].z * yv[j].z + yv[j].w * yv[j].w); }
.LBB0_215:
	s_ashr_i32 s7, s6, 31
	s_lshl_b64 s[12:13], s[6:7], 12
	v_lshl_add_u64 v[0:1], v[44:45], 0, s[12:13]
	global_load_dwordx2 v[4:5], v[0:1], off
	global_load_dwordx2 v[6:7], v[0:1], off offset:512
	global_load_dwordx2 v[12:13], v[0:1], off offset:1024
	global_load_dwordx2 v[14:15], v[0:1], off offset:1536
	global_load_dwordx2 v[16:17], v[0:1], off offset:2048
	global_load_dwordx2 v[18:19], v[0:1], off offset:2560
	global_load_dwordx2 v[20:21], v[0:1], off offset:3072
	global_load_dwordx2 v[22:23], v[0:1], off offset:3584
	v_readlane_b32 s100, v251, 50
	s_cmp_eq_u32 s100, 19
	s_cbranch_scc1 .Lrow_noy1a
	s_mov_b64 s[100:101], 0x4800000
	v_lshl_add_u64 v[130:131], v[0:1], 0, s[100:101]
	global_load_dwordx2 v[132:133], v[130:131], off
	global_load_dwordx2 v[134:135], v[130:131], off offset:512
	global_load_dwordx2 v[136:137], v[130:131], off offset:1024
	global_load_dwordx2 v[138:139], v[130:131], off offset:1536
	global_load_dwordx2 v[140:141], v[130:131], off offset:2048
	global_load_dwordx2 v[142:143], v[130:131], off offset:2560
	global_load_dwordx2 v[144:145], v[130:131], off offset:3072
	global_load_dwordx2 v[146:147], v[130:131], off offset:3584
.Lrow_noy1a:
	global_load_dwordx4 v[8:11], v96, s[24:25]
	s_nop 0
	global_load_dwordx4 v[0:3], v96, s[24:25] offset:1024
	v_cmp_lt_i32_e32 vcc, v211, v212
	s_waitcnt vmcnt(0)
	v_readlane_b32 s100, v251, 50
	s_cmp_eq_u32 s100, 19
	s_cbranch_scc1 .Lrow_noy1b
	v_lshlrev_b32_e32 v150, 16, v4
	v_and_b32_e32 v151, 0xffff0000, v4
	v_lshlrev_b32_e32 v152, 16, v132
	v_and_b32_e32 v153, 0xffff0000, v132
	v_pk_add_f32 v[150:151], v[150:151], v[152:153]
	s_nop 0
	v_cvt_pk_bf16_f32 v4, v150, v151
	v_lshlrev_b32_e32 v154, 16, v5
	v_and_b32_e32 v155, 0xffff0000, v5
	v_lshlrev_b32_e32 v156, 16, v133
	v_and_b32_e32 v157, 0xffff0000, v133
	v_pk_add_f32 v[154:155], v[154:155], v[156:157]
	s_nop 0
	v_cvt_pk_bf16_f32 v5, v154, v155
	v_lshlrev_b32_e32 v150, 16, v6
	v_and_b32_e32 v151, 0xffff0000, v6
	v_lshlrev_b32_e32 v152, 16, v134
	v_and_b32_e32 v153, 0xffff0000, v134
	v_pk_add_f32 v[150:151], v[150:151], v[152:153]
	s_nop 0
	v_cvt_pk_bf16_f32 v6, v150, v151
	v_lshlrev_b32_e32 v154, 16, v7
	v_and_b32_e32 v155, 0xffff0000, v7
	v_lshlrev_b32_e32 v156, 16, v135
	v_and_b32_e32 v157, 0xffff0000, v135
	v_pk_add_f32 v[154:155], v[154:155], v[156:157]
	s_nop 0
	v_cvt_pk_bf16_f32 v7, v154, v155
	v_lshlrev_b32_e32 v150, 16, v12
	v_and_b32_e32 v151, 0xffff0000, v12
	v_lshlrev_b32_e32 v152, 16, v136
	v_and_b32_e32 v153, 0xffff0000, v136
	v_pk_add_f32 v[150:151], v[150:151], v[152:153]
	s_nop 0
	v_cvt_pk_bf16_f32 v12, v150, v151
	v_lshlrev_b32_e32 v154, 16, v13
	v_and_b32_e32 v155, 0xffff0000, v13
	v_lshlrev_b32_e32 v156, 16, v137
	v_and_b32_e32 v157, 0xffff0000, v137
	v_pk_add_f32 v[154:155], v[154:155], v[156:157]
	s_nop 0
	v_cvt_pk_bf16_f32 v13, v154, v155
	v_lshlrev_b32_e32 v150, 16, v14
	v_and_b32_e32 v151, 0xffff0000, v14
	v_lshlrev_b32_e32 v152, 16, v138
	v_and_b32_e32 v153, 0xffff0000, v138
	v_pk_add_f32 v[150:151], v[150:151], v[152:153]
	s_nop 0
	v_cvt_pk_bf16_f32 v14, v150, v151
	v_lshlrev_b32_e32 v154, 16, v15
	v_and_b32_e32 v155, 0xffff0000, v15
	v_lshlrev_b32_e32 v156, 16, v139
	v_and_b32_e32 v157, 0xffff0000, v139
	v_pk_add_f32 v[154:155], v[154:155], v[156:157]
	s_nop 0
	v_cvt_pk_bf16_f32 v15, v154, v155
	v_lshlrev_b32_e32 v150, 16, v16
	v_and_b32_e32 v151, 0xffff0000, v16
	v_lshlrev_b32_e32 v152, 16, v140
	v_and_b32_e32 v153, 0xffff0000, v140
	v_pk_add_f32 v[150:151], v[150:151], v[152:153]
	s_nop 0
	v_cvt_pk_bf16_f32 v16, v150, v151
	v_lshlrev_b32_e32 v154, 16, v17
	v_and_b32_e32 v155, 0xffff0000, v17
	v_lshlrev_b32_e32 v156, 16, v141
	v_and_b32_e32 v157, 0xffff0000, v141
	v_pk_add_f32 v[154:155], v[154:155], v[156:157]
	s_nop 0
	v_cvt_pk_bf16_f32 v17, v154, v155
	v_lshlrev_b32_e32 v150, 16, v18
	v_and_b32_e32 v151, 0xffff0000, v18
	v_lshlrev_b32_e32 v152, 16, v142
	v_and_b32_e32 v153, 0xffff0000, v142
	v_pk_add_f32 v[150:151], v[150:151], v[152:153]
	s_nop 0
	v_cvt_pk_bf16_f32 v18, v150, v151
	v_lshlrev_b32_e32 v154, 16, v19
	v_and_b32_e32 v155, 0xffff0000, v19
	v_lshlrev_b32_e32 v156, 16, v143
	v_and_b32_e32 v157, 0xffff0000, v143
	v_pk_add_f32 v[154:155], v[154:155], v[156:157]
	s_nop 0
	v_cvt_pk_bf16_f32 v19, v154, v155
	v_lshlrev_b32_e32 v150, 16, v20
	v_and_b32_e32 v151, 0xffff0000, v20
	v_lshlrev_b32_e32 v152, 16, v144
	v_and_b32_e32 v153, 0xffff0000, v144
	v_pk_add_f32 v[150:151], v[150:151], v[152:153]
	s_nop 0
	v_cvt_pk_bf16_f32 v20, v150, v151
	v_lshlrev_b32_e32 v154, 16, v21
	v_and_b32_e32 v155, 0xffff0000, v21
	v_lshlrev_b32_e32 v156, 16, v145
	v_and_b32_e32 v157, 0xffff0000, v145
	v_pk_add_f32 v[154:155], v[154:155], v[156:157]
	s_nop 0
	v_cvt_pk_bf16_f32 v21, v154, v155
	v_lshlrev_b32_e32 v150, 16, v22
	v_and_b32_e32 v151, 0xffff0000, v22
	v_lshlrev_b32_e32 v152, 16, v146
	v_and_b32_e32 v153, 0xffff0000, v146
	v_pk_add_f32 v[150:151], v[150:151], v[152:153]
	s_nop 0
	v_cvt_pk_bf16_f32 v22, v150, v151
	v_lshlrev_b32_e32 v154, 16, v23
	v_and_b32_e32 v155, 0xffff0000, v23
	v_lshlrev_b32_e32 v156, 16, v147
	v_and_b32_e32 v157, 0xffff0000, v147
	v_pk_add_f32 v[154:155], v[154:155], v[156:157]
	s_nop 0
	v_cvt_pk_bf16_f32 v23, v154, v155
; __device__ __forceinline__ float bflo(unsigned w) { return __uint_as_float(w << 16); }
; __device__ __forceinline__ float bfhi(unsigned w) { return __uint_as_float(w & 0xffff0000u); }
; __device__ __forceinline__ float wave_sum(float v) {
; #pragma unroll
;     for (int o = 1; o < 64; o <<= 1) v += __shfl_xor(v, o);
;     return v;
; }
; __device__ __forceinline__ void row_phase(const Args& a, int li, LAS unsigned char* lds, int G, int tid, int wave, int lane) {
;     ...
;                 f32x4 yv[8]; float ss = 0.f;
; #pragma unroll
;                 for (int j = 0; j < 8; ++j) { yv[j] = (f32x4){bflo(yw[j].x), bfhi(yw[j].x), bflo(yw[j].y), bfhi(yw[j].y)}; ss += (yv[j].x * yv[j].x + yv[j].y * yv[j].y) + (yv[j].z * yv[j].z + yv[j].w * yv[j].w); }
;                 const float rstd = rsqrtf(wave_sum(ss) * (1.0f / DM) + EPS);
.Lrow_noy1b:
	v_and_b32_e32 v79, 0xffff0000, v4
	v_and_b32_e32 v81, 0xffff0000, v5
	v_lshlrev_b32_e32 v78, 16, v4
	s_waitcnt vmcnt(6)
	v_lshlrev_b32_e32 v55, 16, v14
	v_lshlrev_b32_e32 v80, 16, v5
	v_lshlrev_b32_e32 v83, 16, v7
	v_lshlrev_b32_e32 v82, 16, v6
	v_and_b32_e32 v85, 0xffff0000, v7
	v_and_b32_e32 v84, 0xffff0000, v6
	v_lshlrev_b32_e32 v86, 16, v12
	v_and_b32_e32 v87, 0xffff0000, v12
	v_lshlrev_b32_e32 v88, 16, v13
	v_and_b32_e32 v89, 0xffff0000, v13
	v_and_b32_e32 v31, 0xffff0000, v14
	v_lshlrev_b32_e32 v28, 16, v15
	v_and_b32_e32 v29, 0xffff0000, v15
	s_waitcnt vmcnt(4)
	v_lshlrev_b32_e32 v13, 16, v19
	v_lshlrev_b32_e32 v12, 16, v18
	v_and_b32_e32 v15, 0xffff0000, v19
	v_and_b32_e32 v14, 0xffff0000, v18
	s_waitcnt vmcnt(2)
	v_and_b32_e32 v7, 0xffff0000, v22
	v_mul_f32_e32 v6, v81, v81
	v_mul_f32_e32 v18, v79, v79
	v_mov_b32_e32 v19, v55
	v_lshlrev_b32_e32 v91, 16, v17
	v_lshlrev_b32_e32 v90, 16, v16
	v_and_b32_e32 v93, 0xffff0000, v17
	v_and_b32_e32 v92, 0xffff0000, v16
	v_lshlrev_b32_e32 v53, 16, v22
	v_pk_mul_f32 v[16:17], v[84:85], v[84:85]
	v_pk_fma_f32 v[62:63], v[80:81], v[80:81], v[6:7] op_sel_hi:[1,1,0]
	v_pk_fma_f32 v[64:65], v[78:79], v[78:79], v[18:19] op_sel_hi:[1,1,0]
	v_lshlrev_b32_e32 v24, 16, v20
	v_and_b32_e32 v25, 0xffff0000, v20
	v_lshlrev_b32_e32 v26, 16, v21
	v_and_b32_e32 v27, 0xffff0000, v21
	v_mul_f32_e32 v20, v87, v87
	v_mul_f32_e32 v22, v89, v89
	v_mov_b32_e32 v21, v53
	v_pk_fma_f32 v[16:17], v[82:83], v[82:83], v[16:17]
	v_mov_b32_e32 v54, v64
	v_mov_b32_e32 v18, v62
	v_lshlrev_b32_e32 v4, 16, v23
	v_and_b32_e32 v5, 0xffff0000, v23
	v_mul_f32_e32 v72, v31, v31
	v_mul_f32_e32 v73, v28, v28
	v_mul_f32_e32 v74, v29, v29
	v_pk_fma_f32 v[66:67], v[86:87], v[86:87], v[20:21] op_sel_hi:[1,1,0]
	v_pk_fma_f32 v[22:23], v[88:89], v[88:89], v[22:23] op_sel_hi:[1,1,0]
	v_pk_add_f32 v[62:63], v[64:65], v[62:63]
	v_pk_add_f32 v[16:17], v[16:17], v[16:17] op_sel:[0,1] op_sel_hi:[1,0]
	v_pk_mul_f32 v[18:19], v[54:55], v[18:19]
	v_mov_b32_e32 v67, v73
	v_mov_b32_e32 v23, v74
	v_mov_b32_e32 v17, v72
	v_mov_b32_e32 v63, v19
	v_pk_mul_f32 v[58:59], v[92:93], v[92:93]
	v_pk_add_f32 v[22:23], v[66:67], v[22:23]
	v_pk_add_f32 v[16:17], v[62:63], v[16:17]
	v_pk_fma_f32 v[58:59], v[90:91], v[90:91], v[58:59]
	v_pk_add_f32 v[16:17], v[16:17], v[22:23]
	v_pk_mul_f32 v[60:61], v[14:15], v[14:15]
	v_mul_f32_e32 v52, v27, v27
	v_pk_add_f32 v[58:59], v[58:59], v[58:59] op_sel:[0,1] op_sel_hi:[1,0]
	v_pk_add_f32 v[16:17], v[16:17], v[16:17] op_sel:[0,1] op_sel_hi:[1,0]
	v_mul_f32_e32 v30, v25, v25
	v_pk_fma_f32 v[60:61], v[12:13], v[12:13], v[60:61]
	v_pk_fma_f32 v[70:71], v[26:27], v[26:27], v[52:53] op_sel_hi:[1,1,0]
	v_mov_b32_e32 v20, v58
	v_mov_b32_e32 v52, v16
	v_mul_f32_e32 v75, v7, v7
	v_mul_f32_e32 v76, v4, v4
	v_mul_f32_e32 v77, v5, v5
	v_pk_fma_f32 v[68:69], v[24:25], v[24:25], v[30:31] op_sel_hi:[1,1,0]
	v_pk_add_f32 v[60:61], v[60:61], v[60:61] op_sel:[0,1] op_sel_hi:[1,0]
	v_pk_add_f32 v[16:17], v[16:17], v[58:59]
	v_pk_mul_f32 v[18:19], v[52:53], v[20:21]
	v_mov_b32_e32 v69, v76
	v_mov_b32_e32 v71, v77
	v_mov_b32_e32 v61, v75
	v_mov_b32_e32 v17, v19
	v_pk_add_f32 v[64:65], v[68:69], v[70:71]
	v_pk_add_f32 v[16:17], v[16:17], v[60:61]
	v_lshl_add_u64 v[20:21], s[24:25], 0, v[96:97]
	v_pk_add_f32 v[16:17], v[16:17], v[64:65]
	v_mov_b32_e32 v54, v90
	v_add_f32_e32 v6, v16, v17
	v_cndmask_b32_e32 v16, v210, v211, vcc
	v_lshlrev_b32_e32 v16, 2, v16
	ds_bpermute_b32 v22, v16, v6
	global_load_dwordx4 v[16:19], v96, s[24:25] offset:2048
	global_load_dwordx4 v[58:61], v96, s[24:25] offset:3072
	v_cmp_lt_i32_e32 vcc, v213, v212
	s_waitcnt lgkmcnt(0)
	v_add_f32_e32 v6, v6, v22
	v_cndmask_b32_e32 v22, v210, v213, vcc
	v_add_co_u32_e32 v94, vcc, 0x1000, v20
	v_lshlrev_b32_e32 v22, 2, v22
	s_nop 0
	v_addc_co_u32_e32 v95, vcc, 0, v21, vcc
	global_load_dwordx4 v[62:65], v[94:95], off
	global_load_dwordx4 v[66:69], v[94:95], off offset:1024
	global_load_dwordx4 v[70:73], v[94:95], off offset:2048
	global_load_dwordx4 v[74:77], v[94:95], off offset:3072
	ds_bpermute_b32 v22, v22, v6
	v_cmp_lt_i32_e32 vcc, v214, v212
	s_waitcnt lgkmcnt(0)
; __device__ __forceinline__ void row_phase(const Args& a, int li, LAS unsigned char* lds, int G, int tid, int wave, int lane) {
;     ...
;                 const float rstd = rsqrtf(wave_sum(ss) * (1.0f / DM) + EPS);
; #pragma unroll
;                 for (int j = 0; j < 8; ++j) {
;                     xv[j] += Vr[0 * 512 + 64 * j] * (yv[j] * rstd);
;                     *(f32x4*)(xrow + 4 * lane + 256 * j) = xv[j];
;                 }
	v_add_f32_e32 v6, v6, v22
	v_cndmask_b32_e32 v20, v210, v214, vcc
	v_lshlrev_b32_e32 v20, 2, v20
	ds_bpermute_b32 v20, v20, v6
	v_cmp_lt_i32_e32 vcc, v215, v212
	s_waitcnt lgkmcnt(0)
	v_add_f32_e32 v6, v6, v20
	v_cndmask_b32_e32 v20, v210, v215, vcc
	v_lshlrev_b32_e32 v20, 2, v20
	ds_bpermute_b32 v20, v20, v6
	s_waitcnt lgkmcnt(0)
	v_add_f32_e32 v6, v6, v20
	v_xor_b32_e32 v20, 16, v210
	v_cmp_lt_i32_e32 vcc, v20, v212
	s_nop 1
	v_cndmask_b32_e32 v20, v210, v20, vcc
	v_lshlrev_b32_e32 v20, 2, v20
	ds_bpermute_b32 v20, v20, v6
	s_waitcnt lgkmcnt(0)
	v_add_f32_e32 v6, v6, v20
	v_xor_b32_e32 v20, 32, v210
	v_cmp_lt_i32_e32 vcc, v20, v212
	s_nop 1
	v_cndmask_b32_e32 v20, v210, v20, vcc
	v_lshlrev_b32_e32 v20, 2, v20
	ds_bpermute_b32 v20, v20, v6
	s_waitcnt lgkmcnt(0)
	v_add_f32_e32 v6, v6, v20
	v_fmamk_f32 v6, v6, 0x3a000000, v197
	v_mul_f32_e32 v20, 0x4b800000, v6
	v_cmp_gt_f32_e32 vcc, s21, v6
	s_nop 1
	v_cndmask_b32_e32 v6, v6, v20, vcc
	v_rsq_f32_e32 v6, v6
	ds_read_b128 v[20:23], v57
	v_mul_f32_e32 v30, 0x45800000, v6
	v_cndmask_b32_e32 v52, v6, v30, vcc
	v_pk_mul_f32 v[98:99], v[52:53], v[78:79] op_sel_hi:[0,1]
	v_pk_mul_f32 v[100:101], v[52:53], v[80:81] op_sel_hi:[0,1]
	ds_read_b128 v[78:81], v57 offset:1024
	s_waitcnt vmcnt(7) lgkmcnt(1)
	v_pk_fma_f32 v[20:21], v[20:21], v[98:99], v[8:9]
	v_mov_b32_e32 v8, v82
	v_mov_b32_e32 v9, v84
	v_mov_b32_e32 v84, v83
	v_pk_fma_f32 v[22:23], v[22:23], v[100:101], v[10:11]
	v_pk_mul_f32 v[8:9], v[52:53], v[8:9] op_sel_hi:[0,1]
	v_pk_mul_f32 v[10:11], v[52:53], v[84:85] op_sel_hi:[0,1]
	s_waitcnt vmcnt(6) lgkmcnt(0)
	v_pk_fma_f32 v[10:11], v[80:81], v[10:11], v[2:3]
	v_pk_fma_f32 v[8:9], v[78:79], v[8:9], v[0:1]
	ds_read_b128 v[0:3], v57 offset:2048
	ds_read_b128 v[78:81], v57 offset:3072
	v_pk_mul_f32 v[82:83], v[52:53], v[86:87] op_sel_hi:[0,1]
	v_pk_mul_f32 v[84:85], v[52:53], v[88:89] op_sel_hi:[0,1]
	v_mov_b32_e32 v30, v55
	s_waitcnt vmcnt(5) lgkmcnt(1)
	v_pk_fma_f32 v[18:19], v[2:3], v[84:85], v[18:19]
	v_pk_fma_f32 v[16:17], v[0:1], v[82:83], v[16:17]
	v_pk_mul_f32 v[0:1], v[30:31], v[52:53] op_sel_hi:[1,0]
	v_pk_mul_f32 v[2:3], v[28:29], v[52:53] op_sel_hi:[1,0]
	ds_read_b128 v[28:31], v57 offset:4096
	s_waitcnt vmcnt(4) lgkmcnt(1)
	v_pk_fma_f32 v[2:3], v[80:81], v[2:3], v[60:61]
	v_pk_fma_f32 v[0:1], v[78:79], v[0:1], v[58:59]
	ds_read_b128 v[58:61], v57 offset:5120
	v_mov_b32_e32 v55, v92
	v_pk_mul_f32 v[54:55], v[52:53], v[54:55] op_sel_hi:[0,1]
	v_mov_b32_e32 v92, v91
	s_waitcnt vmcnt(3) lgkmcnt(1)
	v_pk_fma_f32 v[28:29], v[28:29], v[54:55], v[62:63]
	v_mov_b32_e32 v54, v12
	v_mov_b32_e32 v55, v14
	v_mov_b32_e32 v14, v13
	v_pk_mul_f32 v[78:79], v[52:53], v[92:93] op_sel_hi:[0,1]
	v_pk_mul_f32 v[54:55], v[52:53], v[54:55] op_sel_hi:[0,1]
	v_pk_mul_f32 v[12:13], v[52:53], v[14:15] op_sel_hi:[0,1]
	v_pk_fma_f32 v[30:31], v[30:31], v[78:79], v[64:65]
	s_waitcnt vmcnt(2) lgkmcnt(0)
	v_pk_fma_f32 v[14:15], v[60:61], v[12:13], v[68:69]
	v_pk_fma_f32 v[12:13], v[58:59], v[54:55], v[66:67]
	ds_read_b128 v[58:61], v57 offset:6144
	ds_read_b128 v[62:65], v57 offset:7168
	v_mov_b32_e32 v6, v53
	v_pk_mul_f32 v[24:25], v[52:53], v[24:25] op_sel_hi:[0,1]
	v_pk_mul_f32 v[26:27], v[52:53], v[26:27] op_sel_hi:[0,1]
	v_pk_mul_f32 v[54:55], v[6:7], v[52:53] op_sel_hi:[1,0]
	v_pk_mul_f32 v[4:5], v[4:5], v[52:53] op_sel_hi:[1,0]
	s_waitcnt vmcnt(1) lgkmcnt(1)
	v_pk_fma_f32 v[26:27], v[60:61], v[26:27], v[72:73]
	v_pk_fma_f32 v[24:25], v[58:59], v[24:25], v[70:71]
	s_waitcnt vmcnt(0) lgkmcnt(0)
	v_pk_fma_f32 v[6:7], v[64:65], v[4:5], v[76:77]
	v_pk_fma_f32 v[4:5], v[62:63], v[54:55], v[74:75]
	global_store_dwordx4 v96, v[20:23], s[24:25]
	global_store_dwordx4 v96, v[8:11], s[24:25] offset:1024
	global_store_dwordx4 v96, v[16:19], s[24:25] offset:2048
	global_store_dwordx4 v96, v[0:3], s[24:25] offset:3072
	global_store_dwordx4 v[94:95], v[28:31], off
	global_store_dwordx4 v[94:95], v[12:15], off offset:1024
	global_store_dwordx4 v[94:95], v[24:27], off offset:2048
	global_store_dwordx4 v[94:95], v[4:7], off offset:3072
	s_cbranch_execnz .LBB0_214

; #define LAS __attribute__((address_space(3)))
; __device__ __forceinline__ void transpose_layer(const Args& a, int layer, LAS unsigned char* lds, int gw, int NGW, int wave, int lane) {
;     LAS float* scr = (LAS float*)(lds + wave * 16640);
;     bf16_t* WIN = (bf16_t*)(a.ws + WS_WIN); bf16_t* WOUT = (bf16_t*)(a.ws + WS_WOUT); bf16_t* WG = (bf16_t*)(a.ws + WS_WG);
;     const int kind = layer % 3, j = layer / 3;
;     if (kind == 0) {
;         const float* win = a.in[8] + (size_t)j * DM * 16384; const float* wout = a.in[10] + (size_t)j * DI * DM;
;         const int n_in = (DM / 64) * (16384 / 64), n_out = (DI / 64) * (DM / 64);
;         for (int it = gw; it < n_in + n_out; it += NGW) {
;             if (it < n_in) tr_item(win, DM, 16384, WIN, 0x2310, scr, it, lane);
;             else tr_item(wout, DI, DM, WOUT, 0x43210, scr, it - n_in, lane);
;         }
;     } else if (kind == 1) {
;         const float* win = a.in[11]; const float* wg = a.in[12]; const float* wout = a.in[14];
;         const int n_in = (DM / 64) * (8192 / 64), n_g = 16 * 16, n_out = (DI / 64) * (DM / 64);
;         for (int it = gw; it < n_in + 4 * n_g + n_out; it += NGW) {
;             if (it < n_in) tr_item(win, DM, 8192, WIN, 0x43210, scr, it, lane);
;             else if (it < n_in + 4 * n_g) { const int g = (it - n_in) / n_g, r = (it - n_in) % n_g; tr_item(wg + (size_t)g * 1024 * 1024, 1024, 1024, WG + (size_t)g * 1024 * 1024, 0x43210, scr, r, lane); }
;             else tr_item(wout, DI, DM, WOUT, 0x43210, scr, it - n_in - 4 * n_g, lane);
;         }
;     } else {
;         const float* win = a.in[15]; const float* wout = a.in[18];
;         const int n_in = (DM / 64) * (20480 / 64), n_out = (DI / 64) * (DM / 64);
;         for (int it = gw; it < n_in + n_out; it += NGW) {
;             if (it < n_in) tr_item(win, DM, 20480, WIN, 0x34210, scr, it, lane);
;             else tr_item(wout, DI, DM, WOUT, 0x43210, scr, it - n_in, lane);
;         }
.LBB0_218:
	v_readlane_b32 s0, v251, 52
	v_readlane_b32 s4, v251, 54
	v_readlane_b32 s1, v251, 53
	v_readlane_b32 s5, v251, 55
	s_and_b64 s[0:1], s[0:1], s[4:5]
	s_andn2_b64 vcc, exec, s[0:1]
	s_waitcnt lgkmcnt(0)
	s_barrier
	s_cbranch_vccnz .LBB0_250
	v_readlane_b32 s0, v250, 3
	s_mulk_i32 s0, 0x4100
	s_add_i32 s14, s0, 0
	v_readlane_b32 s4, v250, 1
	v_readlane_b32 s5, v250, 2
	s_add_u32 s0, s4, 0x2e00000
	s_addc_u32 s1, s5, 0
	s_add_u32 s4, s4, 0x7e00000
	v_readlane_b32 s6, v250, 4
	s_addc_u32 s5, s5, 0
	v_readlane_b32 s7, v250, 5
	s_and_b64 s[6:7], s[6:7], exec
	v_readlane_b32 s6, v251, 58
	s_cselect_b32 s12, 0, s6
	s_cmp_lt_i32 s12, 1
	s_mov_b64 s[6:7], -1
	s_cbranch_scc1 .LBB0_242
	s_cmp_lg_u32 s12, 1
	s_cbranch_scc0 .LBB0_229
	s_cmpk_gt_i32 s22, 0x2fff
	s_cbranch_scc1 .LBB0_228
	v_readlane_b32 s24, v251, 41
	v_readlane_b32 s26, v251, 43
	v_readlane_b32 s6, v251, 62
	v_readlane_b32 s25, v251, 42
	v_readlane_b32 s27, v251, 44
	v_readlane_b32 s7, v251, 63
	s_add_u32 s15, s26, s6
	s_addc_u32 s18, s27, s7
	v_readlane_b32 s24, v251, 21
	v_readlane_b32 s25, v251, 22
	s_add_u32 s19, s24, s6
	v_lshlrev_b32_e32 v0, 3, v194
	s_addc_u32 s23, s25, s7
	v_lshrrev_b32_e32 v7, 3, v194
	v_and_b32_e32 v0, 56, v0
	v_readlane_b32 s6, v251, 7
	v_readlane_b32 s7, v250, 3
	v_readlane_b32 s26, v251, 23
	v_mul_u32_u24_e32 v2, 0x104, v0
	v_lshlrev_b32_e32 v96, 1, v0
	v_lshlrev_b32_e32 v3, 2, v7
	s_add_i32 s24, s6, s7
	s_lshl_b32 s6, s7, 6
	v_readlane_b32 s7, v252, 7
	v_lshl_add_u32 v6, v194, 2, s14
	v_lshl_add_u64 v[0:1], s[4:5], 0, v[96:97]
	v_add3_u32 v8, s14, v2, v3
	v_lshl_add_u64 v[2:3], s[0:1], 0, v[96:97]
	s_add_i32 s25, s7, s6
	s_mov_b32 s26, s22
	v_readlane_b32 s28, v251, 45
	v_readlane_b32 s29, v251, 46
	v_readlane_b32 s30, v251, 47
	v_readlane_b32 s31, v251, 48
	v_readlane_b32 s27, v251, 24
	s_branch .LBB0_224

; __device__ __forceinline__ void transpose_layer(const Args& a, int layer, LAS unsigned char* lds, int gw, int NGW, int wave, int lane) {
;     ...
;     const int kind = layer % 3, j = layer / 3;
;     if (kind == 0) {
;         const float* win = a.in[8] + (size_t)j * DM * 16384; const float* wout = a.in[10] + (size_t)j * DI * DM;
;         const int n_in = (DM / 64) * (16384 / 64), n_out = (DI / 64) * (DM / 64);
;         for (int it = gw; it < n_in + n_out; it += NGW) {
;             if (it < n_in) tr_item(win, DM, 16384, WIN, 0x2310, scr, it, lane);
;             else tr_item(wout, DI, DM, WOUT, 0x43210, scr, it - n_in, lane);
;         }
.LBB0_242:
	s_andn2_b64 vcc, exec, s[6:7]
	s_cbranch_vccnz .LBB0_250
	s_cmpk_gt_i32 s22, 0x27ff
	s_cbranch_scc1 .LBB0_250
	v_readlane_b32 s12, v250, 4
	v_readlane_b32 s13, v250, 5
	s_and_b64 s[6:7], s[12:13], exec
	s_cselect_b32 s6, 0x8000000, 0
	v_readlane_b32 s7, v251, 59
	s_add_u32 s6, s7, s6
	v_readlane_b32 s7, v251, 60
	s_addc_u32 s7, s7, 0
	v_lshlrev_b32_e32 v0, 3, v194
	s_and_b64 s[12:13], s[12:13], exec
	v_lshrrev_b32_e32 v7, 3, v194
	v_and_b32_e32 v0, 56, v0
	s_cselect_b32 s12, 0x2000000, 0
	v_readlane_b32 s13, v251, 61
	v_mul_u32_u24_e32 v2, 0x104, v0
	v_lshlrev_b32_e32 v96, 1, v0
	v_lshlrev_b32_e32 v3, 2, v7
	s_add_u32 s12, s13, s12
	v_readlane_b32 s13, v250, 0
	v_add3_u32 v8, s14, v2, v3
	v_lshl_add_u64 v[2:3], s[0:1], 0, v[96:97]
	v_readlane_b32 s0, v251, 5
	v_readlane_b32 s1, v250, 3
	s_addc_u32 s13, s13, 0
	v_lshl_add_u32 v6, v194, 2, s14
	s_add_i32 s14, s0, s1
	s_lshl_b32 s0, s1, 6
	v_readlane_b32 s1, v252, 7
	v_lshl_add_u64 v[0:1], s[4:5], 0, v[96:97]
	s_add_i32 s15, s1, s0
	s_mov_b32 s18, s22
	s_branch .LBB0_246

; #define PG8_STAGE(bufoff, gbase, voff) do { _Pragma("unroll") for (int _i = 0; _i < 2; ++_i) \
;         __builtin_amdgcn_global_load_lds((const unsigned*)((const char*)(gbase) + (voff)[_i]), (LAS unsigned*)(lds + (bufoff) + ldsw + _i * 8192), 16, 0, 0); } while (0)
; #define PG8_WAIT_V(n) asm volatile("s_waitcnt vmcnt(" #n ")" ::: "memory")
; #define PG8_BAR __builtin_amdgcn_s_barrier()
; #define PG8_UA(u) unit_a(jt, (u), tstep)
; #define PG8_UB(u) unit_b(jt, (u), tstep)
; __device__ __forceinline__ void gemm_phase(LAS unsigned char* lds, const LAS unsigned char* jt, const int K, const int n0, const int n1, const int G, const int c) {
;     ...
;     PG8_STAGE(PG8_SB(0, 0), cB, voffB); PG8_STAGE(PG8_SB(0, 1), cB + hstep, voffB); PG8_STAGE(PG8_SA(0, 0), cA, voffA); PG8_STAGE(PG8_SA(0, 1), cA + hstep, voffA);
;     if (wr == 1) PG8_BAR;
;     PG8_WAIT_V(2); PG8_BAR;
;     PG8_STAGE(PG8_SB(1, 0), cB + kstep, voffB); PG8_STAGE(PG8_SA(1, 0), cA + kstep, voffA); PG8_STAGE(PG8_SB(1, 1), cB + hstep + kstep, voffB);
;     PG8_WAIT_V(6); PG8_BAR;
;     for (;;) {
;         const bool has_next = next_unit(ui + 1, G, c, jt, n0, n1, nxt);
;         const char* nA = cA; const char* nB = cB;
;         if (has_next) { nA = PG8_UA(nxt); nB = PG8_UB(nxt); }
;         for (int t = 0; t < nt; t += 2) {
;             const bool last = (t == nt - 2);
;             const char* a1 = cA + (size_t)(t + 1) * kstep;
;             const char* a2 = last ? nA : cA + (size_t)(t + 2) * kstep; const char* b2 = last ? nB : cB + (size_t)(t + 2) * kstep;
;             const char* a3 = a2 + kstep; const char* b3 = b2 + kstep;
.LBB0_282:
	s_add_i32 m0, s45, 0x18000
	v_lshl_add_u64 v[0:1], v[0:1], 0, s[80:81]
	s_waitcnt vmcnt(2)
	s_barrier
	global_load_lds_dwordx4 v[0:1], off
	v_lshl_add_u64 v[0:1], v[2:3], 0, s[80:81]
	s_add_i32 m0, s45, 0x1a000
	s_add_i32 s52, s45, 0x8000
	global_load_lds_dwordx4 v[0:1], off
	v_lshl_add_u64 v[0:1], v[8:9], 0, s[80:81]
	s_mov_b32 m0, s52
	s_add_i32 s53, s45, 0xa000
	global_load_lds_dwordx4 v[0:1], off
	v_lshl_add_u64 v[0:1], v[10:11], 0, s[80:81]
	s_mov_b32 m0, s53
	v_bfe_u32 v187, v12, 4, 2
	global_load_lds_dwordx4 v[0:1], off
	s_add_i32 m0, s45, 0x1c000
	v_lshl_add_u64 v[0:1], v[4:5], 0, s[80:81]
	global_load_lds_dwordx4 v[0:1], off
	v_lshl_add_u64 v[0:1], v[6:7], 0, s[80:81]
	s_add_i32 m0, s45, 0x1e000
	v_and_b32_e32 v188, 15, v12
	global_load_lds_dwordx4 v[0:1], off
	v_lshlrev_b32_e32 v19, 4, v187
	v_lshlrev_b32_e32 v12, 2, v12
	s_lshl_b32 s50, s15, 6
	v_lshl_or_b32 v19, v188, 6, v19
	s_lshl_b32 s15, s15, 13
	v_and_b32_e32 v12, 32, v12
	s_lshr_b32 s19, s27, 26
	v_bitop3_b32 v20, v19, s15, v12 bitop3:0xde
	s_lshl_b32 s15, s18, 5
	s_add_i32 s19, s26, s19
	s_and_b32 s51, s15, 0x60
	s_ashr_i32 s49, s19, 6
	v_readlane_b32 s100, v251, 50
	s_mov_b32 s101, 0x4210
	s_bitcmp1_b32 s101, s100
	s_cselect_b32 s101, 1, 0
	s_lshr_b32 s49, s49, s101
	s_lshl_b32 s15, s51, 7
	s_cmp_gt_i32 s26, 63
	v_add_u32_e32 v0, v18, v16
	s_waitcnt vmcnt(6)
	s_cselect_b64 s[28:29], -1, 0
	s_add_i32 s54, s49, -2
	v_add_lshl_u32 v96, v0, v17, 1
	v_add_u32_e32 v0, v15, v13
	s_cmpk_lt_u32 s14, 0x100
	v_lshl_add_u64 v[156:157], s[4:5], 0, v[96:97]
	v_add_lshl_u32 v96, v0, v14, 1
	v_bitop3_b32 v189, v19, s15, v12 bitop3:0xde
	s_cselect_b64 s[38:39], -1, 0
	v_lshl_add_u64 v[158:159], s[4:5], 0, v[96:97]
	s_mov_b32 s55, 0
	v_add_u32_e32 v190, 0, v20
	s_barrier
	s_branch .LBB0_285

; #define LAS __attribute__((address_space(3)))
; __device__ __forceinline__ void transpose_layer(const Args& a, int layer, LAS unsigned char* lds, int gw, int NGW, int wave, int lane) {
;     LAS float* scr = (LAS float*)(lds + wave * 16640);
;     bf16_t* WIN = (bf16_t*)(a.ws + WS_WIN); bf16_t* WOUT = (bf16_t*)(a.ws + WS_WOUT); bf16_t* WG = (bf16_t*)(a.ws + WS_WG);
;     const int kind = layer % 3, j = layer / 3;
;     if (kind == 0) {
;         const float* win = a.in[8] + (size_t)j * DM * 16384; const float* wout = a.in[10] + (size_t)j * DI * DM;
;         const int n_in = (DM / 64) * (16384 / 64), n_out = (DI / 64) * (DM / 64);
;         for (int it = gw; it < n_in + n_out; it += NGW) {
;             if (it < n_in) tr_item(win, DM, 16384, WIN, 0x2310, scr, it, lane);
;             else tr_item(wout, DI, DM, WOUT, 0x43210, scr, it - n_in, lane);
;         }
;     } else if (kind == 1) {
;         const float* win = a.in[11]; const float* wg = a.in[12]; const float* wout = a.in[14];
;         const int n_in = (DM / 64) * (8192 / 64), n_g = 16 * 16, n_out = (DI / 64) * (DM / 64);
;         for (int it = gw; it < n_in + 4 * n_g + n_out; it += NGW) {
;             if (it < n_in) tr_item(win, DM, 8192, WIN, 0x43210, scr, it, lane);
;             else if (it < n_in + 4 * n_g) { const int g = (it - n_in) / n_g, r = (it - n_in) % n_g; tr_item(wg + (size_t)g * 1024 * 1024, 1024, 1024, WG + (size_t)g * 1024 * 1024, 0x43210, scr, r, lane); }
;             else tr_item(wout, DI, DM, WOUT, 0x43210, scr, it - n_in - 4 * n_g, lane);
;         }
.LBB0_421:
	v_readlane_b32 s28, v251, 50
	s_cmp_lg_u32 s28, 4
	s_cbranch_scc1 .Ltr_done
.Ltr_go:
	v_readlane_b32 s15, v251, 49
	v_readlane_b32 s18, v250, 3
	s_cmp_lt_u32 s15, 64
	s_cbranch_scc1 .Ltr_done
	v_writelane_b32 v255, s36, 0
	v_writelane_b32 v255, s37, 1
	v_writelane_b32 v255, s38, 2
	v_writelane_b32 v255, s39, 3
	v_writelane_b32 v255, s40, 4
	v_writelane_b32 v255, s41, 5
	v_writelane_b32 v255, s42, 6
	v_writelane_b32 v255, s43, 7
	v_writelane_b32 v255, s44, 8
	v_writelane_b32 v255, s45, 9
	v_writelane_b32 v255, s46, 10
	v_writelane_b32 v255, s47, 11
	v_writelane_b32 v255, s48, 12
	v_writelane_b32 v255, s49, 13
	v_writelane_b32 v255, s50, 14
	v_writelane_b32 v255, s51, 15
	v_writelane_b32 v255, s52, 16
	v_writelane_b32 v255, s53, 17
	v_writelane_b32 v255, s54, 18
	v_writelane_b32 v255, s55, 19
	v_writelane_b32 v255, s56, 20
	v_writelane_b32 v255, s57, 21
	v_writelane_b32 v255, s58, 22
	v_writelane_b32 v255, s59, 23
	s_sub_i32 s15, s15, 64
	s_lshl_b32 s15, s15, 3
	s_add_i32 s36, s15, s18
	v_readlane_b32 s37, v252, 2
	v_readlane_b32 s40, v252, 0
	v_readlane_b32 s41, v252, 1
	s_sub_i32 s37, s37, 64
	s_lshl_b32 s37, s37, 3
	s_add_u32 s40, s40, 0x2e00000
	s_addc_u32 s41, s41, 0
	v_lshlrev_b32_e32 v80, 2, v210
	v_lshlrev_b32_e32 v81, 12, v210
	s_cmp_eq_u32 s28, 4
	s_cbranch_scc1 .Ltr_p1
	s_cmp_eq_u32 s28, 9
	s_cbranch_scc1 .Ltr_p2
	s_movk_i32 s38, 0x2000
	s_movk_i32 s39, 0x100
	s_mov_b32 s42, 0x1000000
	s_mov_b32 s43, 0x10000
	s_mov_b32 s44, 0x42310
	v_readlane_b32 s46, v251, 13
	v_readlane_b32 s47, v251, 14
	s_add_u32 s46, s46, 0x8000000
	s_addc_u32 s47, s47, 0
	s_branch .Ltr_pdone
